# seam-0 barrier: group size taken from the grid size (grid / 8) instead of the literal 32; otherwise as the guarded one-shot two-level barrier version
# speedup vs baseline: 1.0065x; 1.0016x over previous
; #define LAS __attribute__((address_space(3)))
; #define PH_IDS() int tid = threadIdx.x; asm volatile("" : "+v"(tid)); const int lane = tid & 63
; #define SEAM(k) do { if (IN(k) && IN((k) + 1)) { if ((k) == 0) cg::this_grid().sync(); else xcd_barrier(xbar); } } while (0)
; __global__ void __launch_bounds__(NWAVES * 64, 2) fwd_mega(Args args) {
;     ...
;     { volatile LAS unsigned* m_ = (volatile LAS unsigned*)(lds + MISC_OFF); if (threadIdx.x < 16) m_[threadIdx.x] = 0u; }
;     __syncthreads();
;     if (lo == 0) { unsigned* bz = (unsigned*)(ws + WS_BAR); for (int i = blockIdx.x * (NWAVES * 64) + threadIdx.x; i < BAR_BYTES / 4; i += gridDim.x * (NWAVES * 64)) bz[i] = 0u; }
;     XcdBarrier xbar; xbar.bar = (unsigned*)(ws + WS_BAR); xbar.x = 0; xbar.st = (volatile LAS unsigned*)(lds + MISC_OFF);
;     bf16* XN = (bf16*)args.out;
;     bf16* AO = (bf16*)(ws + WS_AO); bf16* VA = (bf16*)(ws + WS_VA); bf16* ZA = (bf16*)(ws + WS_ZA); bf16* KB = (bf16*)(ws + WS_K); bf16* VB = (bf16*)(ws + WS_V); bf16* ZB = (bf16*)(ws + WS_ZB);
;     bf16* GA = VA; bf16* GB = ZA; bf16* MG = KB;
;     float* ssq = (float*)(ws + WS_SSQ); float* logf_ = (float*)(ws + WS_LOGF); float* cc = (float*)(ws + WS_CC);
;     if (IN(0)) { PH_IDS(); p0_prologue(args, lds, vcu, G, tid, lane, wave); __syncthreads(); }
;     SEAM(0);
.LBB0_62:
	s_cmp_gt_i32 s31, 1
	s_cselect_b64 s[4:5], -1, 0
	s_and_b64 s[0:1], s[22:23], s[4:5]
	s_andn2_b64 vcc, exec, s[0:1]
	v_cmp_eq_u32_e64 s[0:1], 0, v0
	s_cbranch_vccnz .LBB0_74
	s_barrier
	s_and_saveexec_b64 s[6:7], s[0:1]
	s_cbranch_execz .LBB0_73
	buffer_wbl2 sc1
	s_waitcnt vmcnt(0)
	s_add_u32 s8, s28, 0x84000
	s_addc_u32 s9, s29, 0
	s_and_b32 s10, s2, 7
	s_lshl_b32 s10, s10, 8
	s_add_u32 s10, s8, s10
	s_addc_u32 s11, s9, 0
	v_mov_b32_e32 v1, 0
	v_mov_b32_e32 v2, 1
	global_atomic_add v3, v1, v2, s[10:11] offset:32 sc0
	s_waitcnt vmcnt(0)
	v_readfirstlane_b32 s12, v3
	s_lshr_b32 s14, s3, 3
	s_sub_u32 s14, s14, 1
	s_cmp_lg_u32 s12, s14
	s_cbranch_scc1 .Lgs_member
	global_atomic_add v3, v1, v2, s[8:9] offset:2080 sc0
	s_waitcnt vmcnt(0)
	v_readfirstlane_b32 s12, v3
	s_cmp_lg_u32 s12, 7
	s_cbranch_scc1 .Lgs_leader_wait
	global_atomic_add v1, v2, s[8:9] offset:2208
	s_branch .Lgs_leader_go
